# mixer work queue in longest-first order: ret-state, diff-latent, ret-latent, LRU-A, swa-latent, ctx attention, diff-ctx, LRU-B last
# speedup vs baseline: 1.0306x; 1.0050x over previous
.LBB0_855:
	v_add_u32_e32 v0, s3, v196
	v_and_b32_e32 v1, 7, v0
	v_lshlrev_b32_e32 v0, 8, v1
	global_atomic_add v0, v0, v230, s[82:83] sc0
	s_waitcnt vmcnt(0)
	v_add_u32_e32 v2, 0xfffffff0, v0
	v_add_u32_e32 v4, 0xfffffff0, v0
	v_cmp_gt_u32_e32 vcc, 0xe8, v0
	s_nop 1
	v_cndmask_b32_e32 v2, v2, v4, vcc
	v_add_u32_e32 v4, 0x30, v0
	v_cmp_gt_u32_e32 vcc, 0xc8, v0
	s_nop 1
	v_cndmask_b32_e32 v2, v2, v4, vcc
	v_add_u32_e32 v4, 0xfffffff8, v0
	v_cmp_gt_u32_e32 vcc, 0xb8, v0
	s_nop 1
	v_cndmask_b32_e32 v2, v2, v4, vcc
	v_add_u32_e32 v4, 0xfffffff8, v0
	v_cmp_gt_u32_e32 vcc, 0xa8, v0
	s_nop 1
	v_cndmask_b32_e32 v2, v2, v4, vcc
	v_add_u32_e32 v4, 0xfffffff8, v0
	v_cmp_gt_u32_e32 vcc, 0x98, v0
	s_nop 1
	v_cndmask_b32_e32 v2, v2, v4, vcc
	v_add_u32_e32 v4, 0xffffffb8, v0
	v_cmp_gt_u32_e32 vcc, 0x78, v0
	s_nop 1
	v_cndmask_b32_e32 v2, v2, v4, vcc
	v_add_u32_e32 v4, 0xffffffb8, v0
	v_cmp_gt_u32_e32 vcc, 0x68, v0
	s_nop 1
	v_cndmask_b32_e32 v2, v2, v4, vcc
	v_add_u32_e32 v4, 0x28, v0
	v_cmp_gt_u32_e32 vcc, 0x48, v0
	s_nop 1
	v_cndmask_b32_e32 v2, v2, v4, vcc
	v_add_u32_e32 v4, 0x28, v0
	v_cmp_gt_u32_e32 vcc, 0x28, v0
	s_nop 1
	v_cndmask_b32_e32 v2, v2, v4, vcc
	v_add_u32_e32 v4, 0xb0, v0
	v_cmp_gt_u32_e32 vcc, 0x8, v0
	s_nop 1
	v_cndmask_b32_e32 v2, v2, v4, vcc
	v_cmp_gt_u32_e32 vcc, 0xf8, v0
	s_nop 1
	v_cndmask_b32_e32 v0, v0, v2, vcc
	s_nop 1
	v_cmp_lt_i32_e32 vcc, s95, v0
	s_and_saveexec_b64 s[4:5], vcc
	s_xor_b64 s[4:5], exec, s[4:5]
	v_add_u32_e32 v196, 1, v196
	s_or_saveexec_b64 s[4:5], s[4:5]
	v_mov_b32_e32 v197, 0x7d0
	s_xor_b64 exec, exec, s[4:5]
	s_cbranch_execz .LBB0_854
	v_cmp_lt_i32_e32 vcc, 31, v0
	s_and_saveexec_b64 s[10:11], vcc
	s_xor_b64 s[10:11], exec, s[10:11]
	s_cbranch_execz .LBB0_896
	v_cmp_lt_u32_e32 vcc, 47, v0
	s_and_saveexec_b64 s[12:13], vcc
	s_xor_b64 s[12:13], exec, s[12:13]
	s_cbranch_execz .LBB0_893
	s_movk_i32 s14, 0x4f
	v_cmp_lt_u32_e32 vcc, s14, v0
	s_and_saveexec_b64 s[14:15], vcc
	s_xor_b64 s[14:15], exec, s[14:15]
	s_cbranch_execz .LBB0_890
	s_movk_i32 s16, 0x6f
	v_cmp_lt_u32_e32 vcc, s16, v0
	s_and_saveexec_b64 s[16:17], vcc
	s_xor_b64 s[16:17], exec, s[16:17]
	s_cbranch_execz .LBB0_887
	s_movk_i32 s18, 0x8f
	v_cmp_lt_u32_e32 vcc, s18, v0
	s_and_saveexec_b64 s[18:19], vcc
	s_xor_b64 s[18:19], exec, s[18:19]
	s_cbranch_execz .LBB0_884
	s_movk_i32 s20, 0x9f
	v_cmp_lt_u32_e32 vcc, s20, v0
	s_and_saveexec_b64 s[20:21], vcc
	s_xor_b64 s[20:21], exec, s[20:21]
	s_cbranch_execz .LBB0_881
	s_movk_i32 s22, 0xaf
	v_cmp_lt_u32_e32 vcc, s22, v0
	s_and_saveexec_b64 s[22:23], vcc
	s_xor_b64 s[22:23], exec, s[22:23]
	s_cbranch_execz .LBB0_878
	s_movk_i32 s24, 0xb7
	v_cmp_lt_u32_e32 vcc, s24, v0
	s_and_saveexec_b64 s[24:25], vcc
	s_xor_b64 s[24:25], exec, s[24:25]
	s_cbranch_execz .LBB0_875
	s_movk_i32 s33, 0xd7
	v_cmp_lt_u32_e32 vcc, s33, v0
	s_and_saveexec_b64 s[34:35], vcc
	s_xor_b64 s[34:35], exec, s[34:35]
	s_cbranch_execz .LBB0_872
	s_movk_i32 s33, 0xe7
	v_cmp_lt_u32_e32 vcc, s33, v0
	v_lshlrev_b32_e32 v1, 4, v1
	s_and_saveexec_b64 s[44:45], vcc
	s_xor_b64 s[56:57], exec, s[44:45]
	s_movk_i32 s33, 0x668
	v_add3_u32 v197, v0, v1, s33
	s_andn2_saveexec_b64 s[56:57], s[56:57]
	s_movk_i32 s33, 0x5f8
	v_add3_u32 v197, v0, v1, s33
	s_or_b64 exec, exec, s[56:57]

.LBB0_915:
	v_add_u32_e32 v0, s3, v196
	v_and_b32_e32 v1, 7, v0
	v_lshlrev_b32_e32 v0, 8, v1
	global_atomic_add v0, v0, v230, s[82:83] sc0
	s_waitcnt vmcnt(0)
	v_add_u32_e32 v2, 0xfffffff0, v0
	v_add_u32_e32 v4, 0xfffffff0, v0
	v_cmp_gt_u32_e32 vcc, 0xe8, v0
	s_nop 1
	v_cndmask_b32_e32 v2, v2, v4, vcc
	v_add_u32_e32 v4, 0x30, v0
	v_cmp_gt_u32_e32 vcc, 0xc8, v0
	s_nop 1
	v_cndmask_b32_e32 v2, v2, v4, vcc
	v_add_u32_e32 v4, 0xfffffff8, v0
	v_cmp_gt_u32_e32 vcc, 0xb8, v0
	s_nop 1
	v_cndmask_b32_e32 v2, v2, v4, vcc
	v_add_u32_e32 v4, 0xfffffff8, v0
	v_cmp_gt_u32_e32 vcc, 0xa8, v0
	s_nop 1
	v_cndmask_b32_e32 v2, v2, v4, vcc
	v_add_u32_e32 v4, 0xfffffff8, v0
	v_cmp_gt_u32_e32 vcc, 0x98, v0
	s_nop 1
	v_cndmask_b32_e32 v2, v2, v4, vcc
	v_add_u32_e32 v4, 0xffffffb8, v0
	v_cmp_gt_u32_e32 vcc, 0x78, v0
	s_nop 1
	v_cndmask_b32_e32 v2, v2, v4, vcc
	v_add_u32_e32 v4, 0xffffffb8, v0
	v_cmp_gt_u32_e32 vcc, 0x68, v0
	s_nop 1
	v_cndmask_b32_e32 v2, v2, v4, vcc
	v_add_u32_e32 v4, 0x28, v0
	v_cmp_gt_u32_e32 vcc, 0x48, v0
	s_nop 1
	v_cndmask_b32_e32 v2, v2, v4, vcc
	v_add_u32_e32 v4, 0x28, v0
	v_cmp_gt_u32_e32 vcc, 0x28, v0
	s_nop 1
	v_cndmask_b32_e32 v2, v2, v4, vcc
	v_add_u32_e32 v4, 0xb0, v0
	v_cmp_gt_u32_e32 vcc, 0x8, v0
	s_nop 1
	v_cndmask_b32_e32 v2, v2, v4, vcc
	v_cmp_gt_u32_e32 vcc, 0xf8, v0
	s_nop 1
	v_cndmask_b32_e32 v0, v0, v2, vcc
	s_nop 1
	v_cmp_lt_i32_e32 vcc, s95, v0
	s_and_saveexec_b64 s[6:7], vcc
	s_xor_b64 s[6:7], exec, s[6:7]
	v_add_u32_e32 v196, 1, v196
	s_or_saveexec_b64 s[6:7], s[6:7]
	v_mov_b32_e32 v197, 0x7d0
	s_xor_b64 exec, exec, s[6:7]
	s_cbranch_execz .LBB0_914
	v_cmp_lt_i32_e32 vcc, 31, v0
	s_and_saveexec_b64 s[14:15], vcc
	s_xor_b64 s[14:15], exec, s[14:15]
	s_cbranch_execz .LBB0_956
	v_cmp_lt_u32_e32 vcc, 47, v0
	s_and_saveexec_b64 s[16:17], vcc
	s_xor_b64 s[16:17], exec, s[16:17]
	s_cbranch_execz .LBB0_953
	s_movk_i32 s18, 0x4f
	v_cmp_lt_u32_e32 vcc, s18, v0
	s_and_saveexec_b64 s[18:19], vcc
	s_xor_b64 s[18:19], exec, s[18:19]
	s_cbranch_execz .LBB0_950
	s_movk_i32 s20, 0x6f
	v_cmp_lt_u32_e32 vcc, s20, v0
	s_and_saveexec_b64 s[20:21], vcc
	s_xor_b64 s[20:21], exec, s[20:21]
	s_cbranch_execz .LBB0_947
	s_movk_i32 s22, 0x8f
	v_cmp_lt_u32_e32 vcc, s22, v0
	s_and_saveexec_b64 s[22:23], vcc
	s_xor_b64 s[22:23], exec, s[22:23]
	s_cbranch_execz .LBB0_944
	s_movk_i32 s24, 0x9f
	v_cmp_lt_u32_e32 vcc, s24, v0
	s_and_saveexec_b64 s[24:25], vcc
	s_xor_b64 s[24:25], exec, s[24:25]
	s_cbranch_execz .LBB0_941
	s_movk_i32 s33, 0xaf
	v_cmp_lt_u32_e32 vcc, s33, v0
	s_and_saveexec_b64 s[34:35], vcc
	s_xor_b64 s[34:35], exec, s[34:35]
	s_cbranch_execz .LBB0_938
	s_movk_i32 s33, 0xb7
	v_cmp_lt_u32_e32 vcc, s33, v0
	s_and_saveexec_b64 s[44:45], vcc
	s_xor_b64 s[56:57], exec, s[44:45]
	s_cbranch_execz .LBB0_935
	s_movk_i32 s33, 0xd7
	v_cmp_lt_u32_e32 vcc, s33, v0
	s_and_saveexec_b64 s[44:45], vcc
	s_xor_b64 s[76:77], exec, s[44:45]
	s_cbranch_execz .LBB0_932
	s_movk_i32 s33, 0xe7
	v_cmp_lt_u32_e32 vcc, s33, v0
	v_lshlrev_b32_e32 v1, 4, v1
	s_and_saveexec_b64 s[44:45], vcc
	s_xor_b64 s[66:67], exec, s[44:45]
	s_movk_i32 s33, 0x668
	v_add3_u32 v197, v0, v1, s33
	s_andn2_saveexec_b64 s[66:67], s[66:67]
	s_movk_i32 s33, 0x5f8
	v_add3_u32 v197, v0, v1, s33
	s_or_b64 exec, exec, s[66:67]
